# EpiGate math hand-written: conv taps as v_fmac_f32_dpp (no DPP moves / hazard nops), GELU in packed f32 ops
# speedup vs baseline: 1.0167x; 1.0088x over previous
.LBB0_656:
	v_lshlrev_b64 v[60:61], 2, v[208:209]
	v_lshl_add_u64 v[62:63], s[22:23], 0, v[60:61]
	v_lshl_add_u64 v[72:73], s[48:49], 0, v[60:61]
	v_lshl_add_u64 v[80:81], s[50:51], 0, v[60:61]
	v_lshl_add_u64 v[82:83], s[46:47], 0, v[60:61]
	global_load_dwordx4 v[64:67], v[62:63], off offset:16
	global_load_dwordx4 v[84:87], v[62:63], off
	global_load_dwordx4 v[68:71], v[72:73], off offset:16
	global_load_dwordx4 v[88:91], v[72:73], off
	s_nop 0
	global_load_dwordx4 v[72:75], v[80:81], off offset:16
	global_load_dwordx4 v[92:95], v[80:81], off
	global_load_dwordx4 v[60:63], v[82:83], off offset:16
	s_nop 0
	global_load_dwordx4 v[80:83], v[82:83], off
	s_waitcnt lgkmcnt(0)
	s_barrier
	s_and_b64 vcc, exec, s[82:83]
	s_cbranch_vccz .Lgm_z_t0
	ds_read_b128 v[170:173], v228
	ds_read_b128 v[174:177], v228 offset:16
	s_branch .Lgm_l_t0
.Lgm_z_t0:
	v_mov_b32_e32 v170, 0
	v_mov_b32_e32 v171, 0
	v_mov_b32_e32 v172, 0
	v_mov_b32_e32 v173, 0
	v_mov_b32_e32 v174, 0
	v_mov_b32_e32 v175, 0
	v_mov_b32_e32 v176, 0
	v_mov_b32_e32 v177, 0
.Lgm_l_t0:
	v_and_b32_e32 v241, 15, v219
	v_lshl_add_u32 v239, s92, 8, v203
	s_movk_i32 s2, 0x1600
	v_readlane_b32 s0, v253, 8
	v_readlane_b32 s1, v253, 9
	v_lshlrev_b64 v[184:185], 1, v[208:209]
	v_mov_b32_e32 v96, 0xbdd2d3e8
	v_cmp_eq_u32_e32 vcc, 0, v241
	v_lshl_add_u64 v[184:185], s[0:1], 0, v[184:185]
	s_waitcnt vmcnt(0)
	v_cndmask_b32_e32 v231, v179, v84, vcc
	v_cndmask_b32_e32 v232, v179, v85, vcc
	v_cndmask_b32_e32 v233, v179, v86, vcc
	v_cndmask_b32_e32 v234, v179, v87, vcc
	v_cndmask_b32_e32 v235, v179, v64, vcc
	v_cndmask_b32_e32 v236, v179, v65, vcc
	v_cndmask_b32_e32 v237, v179, v66, vcc
	v_cndmask_b32_e32 v238, v179, v67, vcc
	v_cmp_eq_u32_e32 vcc, 15, v241
	s_nop 1
	v_cndmask_b32_e32 v158, v179, v92, vcc
	v_cndmask_b32_e32 v159, v179, v93, vcc
	v_cndmask_b32_e32 v160, v179, v94, vcc
	v_cndmask_b32_e32 v161, v179, v95, vcc
	v_cndmask_b32_e32 v162, v179, v72, vcc
	v_cndmask_b32_e32 v163, v179, v73, vcc
	v_cndmask_b32_e32 v164, v179, v74, vcc
	v_cndmask_b32_e32 v165, v179, v75, vcc
	s_waitcnt lgkmcnt(0)
	v_mov_b32_e32 v244, v80
	v_mov_b32_e32 v245, v81
	v_mov_b32_e32 v246, v82
	v_mov_b32_e32 v247, v83
	v_fmac_f32_dpp v244, v146, v158 row_mirror row_mask:0xf bank_mask:0xf
	v_fmac_f32_dpp v245, v147, v159 row_mirror row_mask:0xf bank_mask:0xf
	v_fmac_f32_dpp v246, v148, v160 row_mirror row_mask:0xf bank_mask:0xf
	v_fmac_f32_dpp v247, v149, v161 row_mirror row_mask:0xf bank_mask:0xf
	v_fmac_f32_dpp v244, v150, v92 row_shl:1 row_mask:0xf bank_mask:0xf
	v_fmac_f32_dpp v245, v151, v93 row_shl:1 row_mask:0xf bank_mask:0xf
	v_fmac_f32_dpp v246, v152, v94 row_shl:1 row_mask:0xf bank_mask:0xf
	v_fmac_f32_dpp v247, v153, v95 row_shl:1 row_mask:0xf bank_mask:0xf
	v_fmac_f32_e32 v244, v88, v150
	v_fmac_f32_e32 v245, v89, v151
	v_fmac_f32_e32 v246, v90, v152
	v_fmac_f32_e32 v247, v91, v153
	v_fmac_f32_dpp v244, v150, v84 row_shr:1 row_mask:0xf bank_mask:0xf
	v_fmac_f32_dpp v245, v151, v85 row_shr:1 row_mask:0xf bank_mask:0xf
	v_fmac_f32_dpp v246, v152, v86 row_shr:1 row_mask:0xf bank_mask:0xf
	v_fmac_f32_dpp v247, v153, v87 row_shr:1 row_mask:0xf bank_mask:0xf
	v_fmac_f32_e32 v244, v170, v231
	v_fmac_f32_e32 v245, v171, v232
	v_fmac_f32_e32 v246, v172, v233
	v_fmac_f32_e32 v247, v173, v234
	v_mov_b32_e32 v248, v60
	v_mov_b32_e32 v249, v61
	v_mov_b32_e32 v250, v62
	v_mov_b32_e32 v251, v63
	v_fmac_f32_dpp v248, v138, v162 row_mirror row_mask:0xf bank_mask:0xf
	v_fmac_f32_dpp v249, v139, v163 row_mirror row_mask:0xf bank_mask:0xf
	v_fmac_f32_dpp v250, v140, v164 row_mirror row_mask:0xf bank_mask:0xf
	v_fmac_f32_dpp v251, v141, v165 row_mirror row_mask:0xf bank_mask:0xf
	v_fmac_f32_dpp v248, v130, v72 row_shl:1 row_mask:0xf bank_mask:0xf
	v_fmac_f32_dpp v249, v131, v73 row_shl:1 row_mask:0xf bank_mask:0xf
	v_fmac_f32_dpp v250, v132, v74 row_shl:1 row_mask:0xf bank_mask:0xf
	v_fmac_f32_dpp v251, v133, v75 row_shl:1 row_mask:0xf bank_mask:0xf
	v_fmac_f32_e32 v248, v68, v130
	v_fmac_f32_e32 v249, v69, v131
	v_fmac_f32_e32 v250, v70, v132
	v_fmac_f32_e32 v251, v71, v133
	v_fmac_f32_dpp v248, v130, v64 row_shr:1 row_mask:0xf bank_mask:0xf
	v_fmac_f32_dpp v249, v131, v65 row_shr:1 row_mask:0xf bank_mask:0xf
	v_fmac_f32_dpp v250, v132, v66 row_shr:1 row_mask:0xf bank_mask:0xf
	v_fmac_f32_dpp v251, v133, v67 row_shr:1 row_mask:0xf bank_mask:0xf
	v_fmac_f32_e32 v248, v174, v235
	v_fmac_f32_e32 v249, v175, v236
	v_fmac_f32_e32 v250, v176, v237
	v_fmac_f32_e32 v251, v177, v238
	v_pk_mul_f32 v[170:171], v[244:245], v[244:245]
	v_pk_mul_f32 v[172:173], v[246:247], v[246:247]
	v_pk_mul_f32 v[174:175], v[248:249], v[248:249]
	v_pk_mul_f32 v[176:177], v[250:251], v[250:251]
	v_pk_fma_f32 v[170:171], v[170:171], v[96:97], v[216:217] op_sel_hi:[1,0,0]
	v_pk_fma_f32 v[172:173], v[172:173], v[96:97], v[216:217] op_sel_hi:[1,0,0]
	v_pk_fma_f32 v[174:175], v[174:175], v[96:97], v[216:217] op_sel_hi:[1,0,0]
	v_pk_fma_f32 v[176:177], v[176:177], v[96:97], v[216:217] op_sel_hi:[1,0,0]
	v_pk_mul_f32 v[170:171], v[244:245], v[170:171]
	v_pk_mul_f32 v[172:173], v[246:247], v[172:173]
	v_pk_mul_f32 v[174:175], v[248:249], v[174:175]
	v_pk_mul_f32 v[176:177], v[250:251], v[176:177]
	v_exp_f32_e32 v170, v170
	v_exp_f32_e32 v171, v171
	v_exp_f32_e32 v172, v172
	v_exp_f32_e32 v173, v173
	v_exp_f32_e32 v174, v174
	v_exp_f32_e32 v175, v175
	v_exp_f32_e32 v176, v176
	v_exp_f32_e32 v177, v177
	v_pk_add_f32 v[170:171], v[170:171], 1.0 op_sel_hi:[1,0]
	v_pk_add_f32 v[172:173], v[172:173], 1.0 op_sel_hi:[1,0]
	v_pk_add_f32 v[174:175], v[174:175], 1.0 op_sel_hi:[1,0]
	v_pk_add_f32 v[176:177], v[176:177], 1.0 op_sel_hi:[1,0]
	v_rcp_f32_e32 v170, v170
	v_rcp_f32_e32 v171, v171
	v_rcp_f32_e32 v172, v172
	v_rcp_f32_e32 v173, v173
	v_rcp_f32_e32 v174, v174
	v_rcp_f32_e32 v175, v175
	v_rcp_f32_e32 v176, v176
	v_rcp_f32_e32 v177, v177
	v_pk_mul_f32 v[244:245], v[244:245], v[170:171]
	v_pk_mul_f32 v[246:247], v[246:247], v[172:173]
	v_pk_mul_f32 v[248:249], v[248:249], v[174:175]
	v_pk_mul_f32 v[250:251], v[250:251], v[176:177]
	v_pk_mul_f32 v[244:245], v[166:167], v[244:245]
	v_pk_mul_f32 v[246:247], v[168:169], v[246:247]
	v_pk_mul_f32 v[248:249], v[154:155], v[248:249]
	v_pk_mul_f32 v[250:251], v[156:157], v[250:251]
	v_add_u32_e32 v97, 0, v239
	v_cvt_pk_bf16_f32 v244, v244, v245
	v_cvt_pk_bf16_f32 v245, v246, v247
	v_mad_u64_u32 v[242:243], vcc, v97, s2, v[184:185]
	v_cvt_pk_bf16_f32 v246, v248, v249
	v_cvt_pk_bf16_f32 v247, v250, v251
	global_store_dwordx4 v[242:243], v[244:247], off
	s_nop 1
	v_mov_b32_e32 v244, v80
	v_mov_b32_e32 v245, v81
	v_mov_b32_e32 v246, v82
	v_mov_b32_e32 v247, v83
	v_fmac_f32_dpp v244, v126, v158 row_mirror row_mask:0xf bank_mask:0xf
	v_fmac_f32_dpp v245, v127, v159 row_mirror row_mask:0xf bank_mask:0xf
	v_fmac_f32_dpp v246, v128, v160 row_mirror row_mask:0xf bank_mask:0xf
	v_fmac_f32_dpp v247, v129, v161 row_mirror row_mask:0xf bank_mask:0xf
	v_fmac_f32_dpp v244, v146, v92 row_shl:1 row_mask:0xf bank_mask:0xf
	v_fmac_f32_dpp v245, v147, v93 row_shl:1 row_mask:0xf bank_mask:0xf
	v_fmac_f32_dpp v246, v148, v94 row_shl:1 row_mask:0xf bank_mask:0xf
	v_fmac_f32_dpp v247, v149, v95 row_shl:1 row_mask:0xf bank_mask:0xf
	v_fmac_f32_e32 v244, v88, v146
	v_fmac_f32_e32 v245, v89, v147
	v_fmac_f32_e32 v246, v90, v148
	v_fmac_f32_e32 v247, v91, v149
	v_fmac_f32_dpp v244, v146, v84 row_shr:1 row_mask:0xf bank_mask:0xf
	v_fmac_f32_dpp v245, v147, v85 row_shr:1 row_mask:0xf bank_mask:0xf
	v_fmac_f32_dpp v246, v148, v86 row_shr:1 row_mask:0xf bank_mask:0xf
	v_fmac_f32_dpp v247, v149, v87 row_shr:1 row_mask:0xf bank_mask:0xf
	v_fmac_f32_dpp v244, v150, v231 row_mirror row_mask:0xf bank_mask:0xf
	v_fmac_f32_dpp v245, v151, v232 row_mirror row_mask:0xf bank_mask:0xf
	v_fmac_f32_dpp v246, v152, v233 row_mirror row_mask:0xf bank_mask:0xf
	v_fmac_f32_dpp v247, v153, v234 row_mirror row_mask:0xf bank_mask:0xf
	v_mov_b32_e32 v248, v60
	v_mov_b32_e32 v249, v61
	v_mov_b32_e32 v250, v62
	v_mov_b32_e32 v251, v63
	v_fmac_f32_dpp v248, v118, v162 row_mirror row_mask:0xf bank_mask:0xf
	v_fmac_f32_dpp v249, v119, v163 row_mirror row_mask:0xf bank_mask:0xf
	v_fmac_f32_dpp v250, v120, v164 row_mirror row_mask:0xf bank_mask:0xf
	v_fmac_f32_dpp v251, v121, v165 row_mirror row_mask:0xf bank_mask:0xf
	v_fmac_f32_dpp v248, v138, v72 row_shl:1 row_mask:0xf bank_mask:0xf
	v_fmac_f32_dpp v249, v139, v73 row_shl:1 row_mask:0xf bank_mask:0xf
	v_fmac_f32_dpp v250, v140, v74 row_shl:1 row_mask:0xf bank_mask:0xf
	v_fmac_f32_dpp v251, v141, v75 row_shl:1 row_mask:0xf bank_mask:0xf
	v_fmac_f32_e32 v248, v68, v138
	v_fmac_f32_e32 v249, v69, v139
	v_fmac_f32_e32 v250, v70, v140
	v_fmac_f32_e32 v251, v71, v141
	v_fmac_f32_dpp v248, v138, v64 row_shr:1 row_mask:0xf bank_mask:0xf
	v_fmac_f32_dpp v249, v139, v65 row_shr:1 row_mask:0xf bank_mask:0xf
	v_fmac_f32_dpp v250, v140, v66 row_shr:1 row_mask:0xf bank_mask:0xf
	v_fmac_f32_dpp v251, v141, v67 row_shr:1 row_mask:0xf bank_mask:0xf
	v_fmac_f32_dpp v248, v130, v235 row_mirror row_mask:0xf bank_mask:0xf
	v_fmac_f32_dpp v249, v131, v236 row_mirror row_mask:0xf bank_mask:0xf
	v_fmac_f32_dpp v250, v132, v237 row_mirror row_mask:0xf bank_mask:0xf
	v_fmac_f32_dpp v251, v133, v238 row_mirror row_mask:0xf bank_mask:0xf
	v_pk_mul_f32 v[170:171], v[244:245], v[244:245]
	v_pk_mul_f32 v[172:173], v[246:247], v[246:247]
	v_pk_mul_f32 v[174:175], v[248:249], v[248:249]
	v_pk_mul_f32 v[176:177], v[250:251], v[250:251]
	v_pk_fma_f32 v[170:171], v[170:171], v[96:97], v[216:217] op_sel_hi:[1,0,0]
	v_pk_fma_f32 v[172:173], v[172:173], v[96:97], v[216:217] op_sel_hi:[1,0,0]
	v_pk_fma_f32 v[174:175], v[174:175], v[96:97], v[216:217] op_sel_hi:[1,0,0]
	v_pk_fma_f32 v[176:177], v[176:177], v[96:97], v[216:217] op_sel_hi:[1,0,0]
	v_pk_mul_f32 v[170:171], v[244:245], v[170:171]
	v_pk_mul_f32 v[172:173], v[246:247], v[172:173]
	v_pk_mul_f32 v[174:175], v[248:249], v[174:175]
	v_pk_mul_f32 v[176:177], v[250:251], v[176:177]
	v_exp_f32_e32 v170, v170
	v_exp_f32_e32 v171, v171
	v_exp_f32_e32 v172, v172
	v_exp_f32_e32 v173, v173
	v_exp_f32_e32 v174, v174
	v_exp_f32_e32 v175, v175
	v_exp_f32_e32 v176, v176
	v_exp_f32_e32 v177, v177
	v_pk_add_f32 v[170:171], v[170:171], 1.0 op_sel_hi:[1,0]
	v_pk_add_f32 v[172:173], v[172:173], 1.0 op_sel_hi:[1,0]
	v_pk_add_f32 v[174:175], v[174:175], 1.0 op_sel_hi:[1,0]
	v_pk_add_f32 v[176:177], v[176:177], 1.0 op_sel_hi:[1,0]
	v_rcp_f32_e32 v170, v170
	v_rcp_f32_e32 v171, v171
	v_rcp_f32_e32 v172, v172
	v_rcp_f32_e32 v173, v173
	v_rcp_f32_e32 v174, v174
	v_rcp_f32_e32 v175, v175
	v_rcp_f32_e32 v176, v176
	v_rcp_f32_e32 v177, v177
	v_pk_mul_f32 v[244:245], v[244:245], v[170:171]
	v_pk_mul_f32 v[246:247], v[246:247], v[172:173]
	v_pk_mul_f32 v[248:249], v[248:249], v[174:175]
	v_pk_mul_f32 v[250:251], v[250:251], v[176:177]
	v_pk_mul_f32 v[244:245], v[142:143], v[244:245]
	v_pk_mul_f32 v[246:247], v[144:145], v[246:247]
	v_pk_mul_f32 v[248:249], v[134:135], v[248:249]
	v_pk_mul_f32 v[250:251], v[136:137], v[250:251]
	v_add_u32_e32 v97, 16, v239
	v_cvt_pk_bf16_f32 v244, v244, v245
	v_cvt_pk_bf16_f32 v245, v246, v247
	v_mad_u64_u32 v[242:243], vcc, v97, s2, v[184:185]
	v_cvt_pk_bf16_f32 v246, v248, v249
	v_cvt_pk_bf16_f32 v247, v250, v251
	global_store_dwordx4 v[242:243], v[244:247], off
	s_nop 1
	v_mov_b32_e32 v244, v80
	v_mov_b32_e32 v245, v81
	v_mov_b32_e32 v246, v82
	v_mov_b32_e32 v247, v83
	v_fmac_f32_dpp v244, v110, v158 row_mirror row_mask:0xf bank_mask:0xf
	v_fmac_f32_dpp v245, v111, v159 row_mirror row_mask:0xf bank_mask:0xf
	v_fmac_f32_dpp v246, v112, v160 row_mirror row_mask:0xf bank_mask:0xf
	v_fmac_f32_dpp v247, v113, v161 row_mirror row_mask:0xf bank_mask:0xf
	v_fmac_f32_dpp v244, v126, v92 row_shl:1 row_mask:0xf bank_mask:0xf
	v_fmac_f32_dpp v245, v127, v93 row_shl:1 row_mask:0xf bank_mask:0xf
	v_fmac_f32_dpp v246, v128, v94 row_shl:1 row_mask:0xf bank_mask:0xf
	v_fmac_f32_dpp v247, v129, v95 row_shl:1 row_mask:0xf bank_mask:0xf
	v_fmac_f32_e32 v244, v88, v126
	v_fmac_f32_e32 v245, v89, v127
	v_fmac_f32_e32 v246, v90, v128
	v_fmac_f32_e32 v247, v91, v129
	v_fmac_f32_dpp v244, v126, v84 row_shr:1 row_mask:0xf bank_mask:0xf
	v_fmac_f32_dpp v245, v127, v85 row_shr:1 row_mask:0xf bank_mask:0xf
	v_fmac_f32_dpp v246, v128, v86 row_shr:1 row_mask:0xf bank_mask:0xf
	v_fmac_f32_dpp v247, v129, v87 row_shr:1 row_mask:0xf bank_mask:0xf
	v_fmac_f32_dpp v244, v146, v231 row_mirror row_mask:0xf bank_mask:0xf
	v_fmac_f32_dpp v245, v147, v232 row_mirror row_mask:0xf bank_mask:0xf
	v_fmac_f32_dpp v246, v148, v233 row_mirror row_mask:0xf bank_mask:0xf
	v_fmac_f32_dpp v247, v149, v234 row_mirror row_mask:0xf bank_mask:0xf
	v_mov_b32_e32 v248, v60
	v_mov_b32_e32 v249, v61
	v_mov_b32_e32 v250, v62
	v_mov_b32_e32 v251, v63
	v_fmac_f32_dpp v248, v98, v162 row_mirror row_mask:0xf bank_mask:0xf
	v_fmac_f32_dpp v249, v99, v163 row_mirror row_mask:0xf bank_mask:0xf
	v_fmac_f32_dpp v250, v100, v164 row_mirror row_mask:0xf bank_mask:0xf
	v_fmac_f32_dpp v251, v101, v165 row_mirror row_mask:0xf bank_mask:0xf
	v_fmac_f32_dpp v248, v118, v72 row_shl:1 row_mask:0xf bank_mask:0xf
	v_fmac_f32_dpp v249, v119, v73 row_shl:1 row_mask:0xf bank_mask:0xf
	v_fmac_f32_dpp v250, v120, v74 row_shl:1 row_mask:0xf bank_mask:0xf
	v_fmac_f32_dpp v251, v121, v75 row_shl:1 row_mask:0xf bank_mask:0xf
	v_fmac_f32_e32 v248, v68, v118
	v_fmac_f32_e32 v249, v69, v119
	v_fmac_f32_e32 v250, v70, v120
	v_fmac_f32_e32 v251, v71, v121
	v_fmac_f32_dpp v248, v118, v64 row_shr:1 row_mask:0xf bank_mask:0xf
	v_fmac_f32_dpp v249, v119, v65 row_shr:1 row_mask:0xf bank_mask:0xf
	v_fmac_f32_dpp v250, v120, v66 row_shr:1 row_mask:0xf bank_mask:0xf
	v_fmac_f32_dpp v251, v121, v67 row_shr:1 row_mask:0xf bank_mask:0xf
	v_fmac_f32_dpp v248, v138, v235 row_mirror row_mask:0xf bank_mask:0xf
	v_fmac_f32_dpp v249, v139, v236 row_mirror row_mask:0xf bank_mask:0xf
	v_fmac_f32_dpp v250, v140, v237 row_mirror row_mask:0xf bank_mask:0xf
	v_fmac_f32_dpp v251, v141, v238 row_mirror row_mask:0xf bank_mask:0xf
	v_pk_mul_f32 v[170:171], v[244:245], v[244:245]
	v_pk_mul_f32 v[172:173], v[246:247], v[246:247]
	v_pk_mul_f32 v[174:175], v[248:249], v[248:249]
	v_pk_mul_f32 v[176:177], v[250:251], v[250:251]
	v_pk_fma_f32 v[170:171], v[170:171], v[96:97], v[216:217] op_sel_hi:[1,0,0]
	v_pk_fma_f32 v[172:173], v[172:173], v[96:97], v[216:217] op_sel_hi:[1,0,0]
	v_pk_fma_f32 v[174:175], v[174:175], v[96:97], v[216:217] op_sel_hi:[1,0,0]
	v_pk_fma_f32 v[176:177], v[176:177], v[96:97], v[216:217] op_sel_hi:[1,0,0]
	v_pk_mul_f32 v[170:171], v[244:245], v[170:171]
	v_pk_mul_f32 v[172:173], v[246:247], v[172:173]
	v_pk_mul_f32 v[174:175], v[248:249], v[174:175]
	v_pk_mul_f32 v[176:177], v[250:251], v[176:177]
	v_exp_f32_e32 v170, v170
	v_exp_f32_e32 v171, v171
	v_exp_f32_e32 v172, v172
	v_exp_f32_e32 v173, v173
	v_exp_f32_e32 v174, v174
	v_exp_f32_e32 v175, v175
	v_exp_f32_e32 v176, v176
	v_exp_f32_e32 v177, v177
	v_pk_add_f32 v[170:171], v[170:171], 1.0 op_sel_hi:[1,0]
	v_pk_add_f32 v[172:173], v[172:173], 1.0 op_sel_hi:[1,0]
	v_pk_add_f32 v[174:175], v[174:175], 1.0 op_sel_hi:[1,0]
	v_pk_add_f32 v[176:177], v[176:177], 1.0 op_sel_hi:[1,0]
	v_rcp_f32_e32 v170, v170
	v_rcp_f32_e32 v171, v171
	v_rcp_f32_e32 v172, v172
	v_rcp_f32_e32 v173, v173
	v_rcp_f32_e32 v174, v174
	v_rcp_f32_e32 v175, v175
	v_rcp_f32_e32 v176, v176
	v_rcp_f32_e32 v177, v177
	v_pk_mul_f32 v[244:245], v[244:245], v[170:171]
	v_pk_mul_f32 v[246:247], v[246:247], v[172:173]
	v_pk_mul_f32 v[248:249], v[248:249], v[174:175]
	v_pk_mul_f32 v[250:251], v[250:251], v[176:177]
	v_pk_mul_f32 v[244:245], v[122:123], v[244:245]
	v_pk_mul_f32 v[246:247], v[124:125], v[246:247]
	v_pk_mul_f32 v[248:249], v[114:115], v[248:249]
	v_pk_mul_f32 v[250:251], v[116:117], v[250:251]
	v_add_u32_e32 v97, 32, v239
	v_cvt_pk_bf16_f32 v244, v244, v245
	v_cvt_pk_bf16_f32 v245, v246, v247
	v_mad_u64_u32 v[242:243], vcc, v97, s2, v[184:185]
	v_cvt_pk_bf16_f32 v246, v248, v249
	v_cvt_pk_bf16_f32 v247, v250, v251
	global_store_dwordx4 v[242:243], v[244:247], off
	s_nop 1
	s_and_b64 vcc, exec, s[84:85]
	s_cbranch_vccz .Lgm_z_b0
	ds_read_b128 v[170:173], v212 offset:1024
	ds_read_b128 v[174:177], v212 offset:1040
	s_branch .Lgm_l_b0

.Lgm_l_b0:
	s_waitcnt lgkmcnt(0)
	v_fma_f32 v244, v170, v158, v80
	v_fma_f32 v245, v171, v159, v81
	v_fma_f32 v246, v172, v160, v82
	v_fma_f32 v247, v173, v161, v83
	v_fmac_f32_dpp v244, v110, v92 row_shl:1 row_mask:0xf bank_mask:0xf
	v_fmac_f32_dpp v245, v111, v93 row_shl:1 row_mask:0xf bank_mask:0xf
	v_fmac_f32_dpp v246, v112, v94 row_shl:1 row_mask:0xf bank_mask:0xf
	v_fmac_f32_dpp v247, v113, v95 row_shl:1 row_mask:0xf bank_mask:0xf
	v_fmac_f32_e32 v244, v88, v110
	v_fmac_f32_e32 v245, v89, v111
	v_fmac_f32_e32 v246, v90, v112
	v_fmac_f32_e32 v247, v91, v113
	v_fmac_f32_dpp v244, v110, v84 row_shr:1 row_mask:0xf bank_mask:0xf
	v_fmac_f32_dpp v245, v111, v85 row_shr:1 row_mask:0xf bank_mask:0xf
	v_fmac_f32_dpp v246, v112, v86 row_shr:1 row_mask:0xf bank_mask:0xf
	v_fmac_f32_dpp v247, v113, v87 row_shr:1 row_mask:0xf bank_mask:0xf
	v_fmac_f32_dpp v244, v126, v231 row_mirror row_mask:0xf bank_mask:0xf
	v_fmac_f32_dpp v245, v127, v232 row_mirror row_mask:0xf bank_mask:0xf
	v_fmac_f32_dpp v246, v128, v233 row_mirror row_mask:0xf bank_mask:0xf
	v_fmac_f32_dpp v247, v129, v234 row_mirror row_mask:0xf bank_mask:0xf
	v_fma_f32 v248, v174, v162, v60
	v_fma_f32 v249, v175, v163, v61
	v_fma_f32 v250, v176, v164, v62
	v_fma_f32 v251, v177, v165, v63
	v_fmac_f32_dpp v248, v98, v72 row_shl:1 row_mask:0xf bank_mask:0xf
	v_fmac_f32_dpp v249, v99, v73 row_shl:1 row_mask:0xf bank_mask:0xf
	v_fmac_f32_dpp v250, v100, v74 row_shl:1 row_mask:0xf bank_mask:0xf
	v_fmac_f32_dpp v251, v101, v75 row_shl:1 row_mask:0xf bank_mask:0xf
	v_fmac_f32_e32 v248, v68, v98
	v_fmac_f32_e32 v249, v69, v99
	v_fmac_f32_e32 v250, v70, v100
	v_fmac_f32_e32 v251, v71, v101
	v_fmac_f32_dpp v248, v98, v64 row_shr:1 row_mask:0xf bank_mask:0xf
	v_fmac_f32_dpp v249, v99, v65 row_shr:1 row_mask:0xf bank_mask:0xf
	v_fmac_f32_dpp v250, v100, v66 row_shr:1 row_mask:0xf bank_mask:0xf
	v_fmac_f32_dpp v251, v101, v67 row_shr:1 row_mask:0xf bank_mask:0xf
	v_fmac_f32_dpp v248, v118, v235 row_mirror row_mask:0xf bank_mask:0xf
	v_fmac_f32_dpp v249, v119, v236 row_mirror row_mask:0xf bank_mask:0xf
	v_fmac_f32_dpp v250, v120, v237 row_mirror row_mask:0xf bank_mask:0xf
	v_fmac_f32_dpp v251, v121, v238 row_mirror row_mask:0xf bank_mask:0xf
	v_pk_mul_f32 v[170:171], v[244:245], v[244:245]
	v_pk_mul_f32 v[172:173], v[246:247], v[246:247]
	v_pk_mul_f32 v[174:175], v[248:249], v[248:249]
	v_pk_mul_f32 v[176:177], v[250:251], v[250:251]
	v_pk_fma_f32 v[170:171], v[170:171], v[96:97], v[216:217] op_sel_hi:[1,0,0]
	v_pk_fma_f32 v[172:173], v[172:173], v[96:97], v[216:217] op_sel_hi:[1,0,0]
	v_pk_fma_f32 v[174:175], v[174:175], v[96:97], v[216:217] op_sel_hi:[1,0,0]
	v_pk_fma_f32 v[176:177], v[176:177], v[96:97], v[216:217] op_sel_hi:[1,0,0]
	v_pk_mul_f32 v[170:171], v[244:245], v[170:171]
	v_pk_mul_f32 v[172:173], v[246:247], v[172:173]
	v_pk_mul_f32 v[174:175], v[248:249], v[174:175]
	v_pk_mul_f32 v[176:177], v[250:251], v[176:177]
	v_exp_f32_e32 v170, v170
	v_exp_f32_e32 v171, v171
	v_exp_f32_e32 v172, v172
	v_exp_f32_e32 v173, v173
	v_exp_f32_e32 v174, v174
	v_exp_f32_e32 v175, v175
	v_exp_f32_e32 v176, v176
	v_exp_f32_e32 v177, v177
	v_pk_add_f32 v[170:171], v[170:171], 1.0 op_sel_hi:[1,0]
	v_pk_add_f32 v[172:173], v[172:173], 1.0 op_sel_hi:[1,0]
	v_pk_add_f32 v[174:175], v[174:175], 1.0 op_sel_hi:[1,0]
	v_pk_add_f32 v[176:177], v[176:177], 1.0 op_sel_hi:[1,0]
	v_rcp_f32_e32 v170, v170
	v_rcp_f32_e32 v171, v171
	v_rcp_f32_e32 v172, v172
	v_rcp_f32_e32 v173, v173
	v_rcp_f32_e32 v174, v174
	v_rcp_f32_e32 v175, v175
	v_rcp_f32_e32 v176, v176
	v_rcp_f32_e32 v177, v177
	v_pk_mul_f32 v[244:245], v[244:245], v[170:171]
	v_pk_mul_f32 v[246:247], v[246:247], v[172:173]
	v_pk_mul_f32 v[248:249], v[248:249], v[174:175]
	v_pk_mul_f32 v[250:251], v[250:251], v[176:177]
	v_pk_mul_f32 v[244:245], v[106:107], v[244:245]
	v_pk_mul_f32 v[246:247], v[108:109], v[246:247]
	v_pk_mul_f32 v[248:249], v[102:103], v[248:249]
	v_pk_mul_f32 v[250:251], v[104:105], v[250:251]
	v_add_u32_e32 v97, 48, v239
	v_cvt_pk_bf16_f32 v244, v244, v245
	v_cvt_pk_bf16_f32 v245, v246, v247
	v_mad_u64_u32 v[242:243], vcc, v97, s2, v[184:185]
	v_cvt_pk_bf16_f32 v246, v248, v249
	v_cvt_pk_bf16_f32 v247, v250, v251
	global_store_dwordx4 v[242:243], v[244:247], off
	s_nop 1
	s_and_b64 vcc, exec, s[86:87]
	s_cbranch_vccz .Lgm_z_t1
	ds_read_b128 v[170:173], v229
	ds_read_b128 v[174:177], v229 offset:16
	s_branch .Lgm_l_t1

.Lgm_l_t1:
	s_waitcnt lgkmcnt(0)
	v_mov_b32_e32 v244, v80
	v_mov_b32_e32 v245, v81
	v_mov_b32_e32 v246, v82
	v_mov_b32_e32 v247, v83
	v_fmac_f32_dpp v244, v48, v158 row_mirror row_mask:0xf bank_mask:0xf
	v_fmac_f32_dpp v245, v49, v159 row_mirror row_mask:0xf bank_mask:0xf
	v_fmac_f32_dpp v246, v50, v160 row_mirror row_mask:0xf bank_mask:0xf
	v_fmac_f32_dpp v247, v51, v161 row_mirror row_mask:0xf bank_mask:0xf
	v_fmac_f32_dpp v244, v52, v92 row_shl:1 row_mask:0xf bank_mask:0xf
	v_fmac_f32_dpp v245, v53, v93 row_shl:1 row_mask:0xf bank_mask:0xf
	v_fmac_f32_dpp v246, v54, v94 row_shl:1 row_mask:0xf bank_mask:0xf
	v_fmac_f32_dpp v247, v55, v95 row_shl:1 row_mask:0xf bank_mask:0xf
	v_fmac_f32_e32 v244, v88, v52
	v_fmac_f32_e32 v245, v89, v53
	v_fmac_f32_e32 v246, v90, v54
	v_fmac_f32_e32 v247, v91, v55
	v_fmac_f32_dpp v244, v52, v84 row_shr:1 row_mask:0xf bank_mask:0xf
	v_fmac_f32_dpp v245, v53, v85 row_shr:1 row_mask:0xf bank_mask:0xf
	v_fmac_f32_dpp v246, v54, v86 row_shr:1 row_mask:0xf bank_mask:0xf
	v_fmac_f32_dpp v247, v55, v87 row_shr:1 row_mask:0xf bank_mask:0xf
	v_fmac_f32_e32 v244, v170, v231
	v_fmac_f32_e32 v245, v171, v232
	v_fmac_f32_e32 v246, v172, v233
	v_fmac_f32_e32 v247, v173, v234
	v_mov_b32_e32 v248, v60
	v_mov_b32_e32 v249, v61
	v_mov_b32_e32 v250, v62
	v_mov_b32_e32 v251, v63
	v_fmac_f32_dpp v248, v40, v162 row_mirror row_mask:0xf bank_mask:0xf
	v_fmac_f32_dpp v249, v41, v163 row_mirror row_mask:0xf bank_mask:0xf
	v_fmac_f32_dpp v250, v42, v164 row_mirror row_mask:0xf bank_mask:0xf
	v_fmac_f32_dpp v251, v43, v165 row_mirror row_mask:0xf bank_mask:0xf
	v_fmac_f32_dpp v248, v36, v72 row_shl:1 row_mask:0xf bank_mask:0xf
	v_fmac_f32_dpp v249, v37, v73 row_shl:1 row_mask:0xf bank_mask:0xf
	v_fmac_f32_dpp v250, v38, v74 row_shl:1 row_mask:0xf bank_mask:0xf
	v_fmac_f32_dpp v251, v39, v75 row_shl:1 row_mask:0xf bank_mask:0xf
	v_fmac_f32_e32 v248, v68, v36
	v_fmac_f32_e32 v249, v69, v37
	v_fmac_f32_e32 v250, v70, v38
	v_fmac_f32_e32 v251, v71, v39
	v_fmac_f32_dpp v248, v36, v64 row_shr:1 row_mask:0xf bank_mask:0xf
	v_fmac_f32_dpp v249, v37, v65 row_shr:1 row_mask:0xf bank_mask:0xf
	v_fmac_f32_dpp v250, v38, v66 row_shr:1 row_mask:0xf bank_mask:0xf
	v_fmac_f32_dpp v251, v39, v67 row_shr:1 row_mask:0xf bank_mask:0xf
	v_fmac_f32_e32 v248, v174, v235
	v_fmac_f32_e32 v249, v175, v236
	v_fmac_f32_e32 v250, v176, v237
	v_fmac_f32_e32 v251, v177, v238
	v_pk_mul_f32 v[170:171], v[244:245], v[244:245]
	v_pk_mul_f32 v[172:173], v[246:247], v[246:247]
	v_pk_mul_f32 v[174:175], v[248:249], v[248:249]
	v_pk_mul_f32 v[176:177], v[250:251], v[250:251]
	v_pk_fma_f32 v[170:171], v[170:171], v[96:97], v[216:217] op_sel_hi:[1,0,0]
	v_pk_fma_f32 v[172:173], v[172:173], v[96:97], v[216:217] op_sel_hi:[1,0,0]
	v_pk_fma_f32 v[174:175], v[174:175], v[96:97], v[216:217] op_sel_hi:[1,0,0]
	v_pk_fma_f32 v[176:177], v[176:177], v[96:97], v[216:217] op_sel_hi:[1,0,0]
	v_pk_mul_f32 v[170:171], v[244:245], v[170:171]
	v_pk_mul_f32 v[172:173], v[246:247], v[172:173]
	v_pk_mul_f32 v[174:175], v[248:249], v[174:175]
	v_pk_mul_f32 v[176:177], v[250:251], v[176:177]
	v_exp_f32_e32 v170, v170
	v_exp_f32_e32 v171, v171
	v_exp_f32_e32 v172, v172
	v_exp_f32_e32 v173, v173
	v_exp_f32_e32 v174, v174
	v_exp_f32_e32 v175, v175
	v_exp_f32_e32 v176, v176
	v_exp_f32_e32 v177, v177
	v_pk_add_f32 v[170:171], v[170:171], 1.0 op_sel_hi:[1,0]
	v_pk_add_f32 v[172:173], v[172:173], 1.0 op_sel_hi:[1,0]
	v_pk_add_f32 v[174:175], v[174:175], 1.0 op_sel_hi:[1,0]
	v_pk_add_f32 v[176:177], v[176:177], 1.0 op_sel_hi:[1,0]
	v_rcp_f32_e32 v170, v170
	v_rcp_f32_e32 v171, v171
	v_rcp_f32_e32 v172, v172
	v_rcp_f32_e32 v173, v173
	v_rcp_f32_e32 v174, v174
	v_rcp_f32_e32 v175, v175
	v_rcp_f32_e32 v176, v176
	v_rcp_f32_e32 v177, v177
	v_pk_mul_f32 v[244:245], v[244:245], v[170:171]
	v_pk_mul_f32 v[246:247], v[246:247], v[172:173]
	v_pk_mul_f32 v[248:249], v[248:249], v[174:175]
	v_pk_mul_f32 v[250:251], v[250:251], v[176:177]
	v_pk_mul_f32 v[244:245], v[76:77], v[244:245]
	v_pk_mul_f32 v[246:247], v[78:79], v[246:247]
	v_pk_mul_f32 v[248:249], v[56:57], v[248:249]
	v_pk_mul_f32 v[250:251], v[58:59], v[250:251]
	v_add_u32_e32 v97, 128, v239
	v_cvt_pk_bf16_f32 v244, v244, v245
	v_cvt_pk_bf16_f32 v245, v246, v247
	v_mad_u64_u32 v[242:243], vcc, v97, s2, v[184:185]
	v_cvt_pk_bf16_f32 v246, v248, v249
	v_cvt_pk_bf16_f32 v247, v250, v251
	global_store_dwordx4 v[242:243], v[244:247], off
	s_nop 1
	v_mov_b32_e32 v244, v80
	v_mov_b32_e32 v245, v81
	v_mov_b32_e32 v246, v82
	v_mov_b32_e32 v247, v83
	v_fmac_f32_dpp v244, v28, v158 row_mirror row_mask:0xf bank_mask:0xf
	v_fmac_f32_dpp v245, v29, v159 row_mirror row_mask:0xf bank_mask:0xf
	v_fmac_f32_dpp v246, v30, v160 row_mirror row_mask:0xf bank_mask:0xf
	v_fmac_f32_dpp v247, v31, v161 row_mirror row_mask:0xf bank_mask:0xf
	v_fmac_f32_dpp v244, v48, v92 row_shl:1 row_mask:0xf bank_mask:0xf
	v_fmac_f32_dpp v245, v49, v93 row_shl:1 row_mask:0xf bank_mask:0xf
	v_fmac_f32_dpp v246, v50, v94 row_shl:1 row_mask:0xf bank_mask:0xf
	v_fmac_f32_dpp v247, v51, v95 row_shl:1 row_mask:0xf bank_mask:0xf
	v_fmac_f32_e32 v244, v88, v48
	v_fmac_f32_e32 v245, v89, v49
	v_fmac_f32_e32 v246, v90, v50
	v_fmac_f32_e32 v247, v91, v51
	v_fmac_f32_dpp v244, v48, v84 row_shr:1 row_mask:0xf bank_mask:0xf
	v_fmac_f32_dpp v245, v49, v85 row_shr:1 row_mask:0xf bank_mask:0xf
	v_fmac_f32_dpp v246, v50, v86 row_shr:1 row_mask:0xf bank_mask:0xf
	v_fmac_f32_dpp v247, v51, v87 row_shr:1 row_mask:0xf bank_mask:0xf
	v_fmac_f32_dpp v244, v52, v231 row_mirror row_mask:0xf bank_mask:0xf
	v_fmac_f32_dpp v245, v53, v232 row_mirror row_mask:0xf bank_mask:0xf
	v_fmac_f32_dpp v246, v54, v233 row_mirror row_mask:0xf bank_mask:0xf
	v_fmac_f32_dpp v247, v55, v234 row_mirror row_mask:0xf bank_mask:0xf
	v_mov_b32_e32 v248, v60
	v_mov_b32_e32 v249, v61
	v_mov_b32_e32 v250, v62
	v_mov_b32_e32 v251, v63
	v_fmac_f32_dpp v248, v20, v162 row_mirror row_mask:0xf bank_mask:0xf
	v_fmac_f32_dpp v249, v21, v163 row_mirror row_mask:0xf bank_mask:0xf
	v_fmac_f32_dpp v250, v22, v164 row_mirror row_mask:0xf bank_mask:0xf
	v_fmac_f32_dpp v251, v23, v165 row_mirror row_mask:0xf bank_mask:0xf
	v_fmac_f32_dpp v248, v40, v72 row_shl:1 row_mask:0xf bank_mask:0xf
	v_fmac_f32_dpp v249, v41, v73 row_shl:1 row_mask:0xf bank_mask:0xf
	v_fmac_f32_dpp v250, v42, v74 row_shl:1 row_mask:0xf bank_mask:0xf
	v_fmac_f32_dpp v251, v43, v75 row_shl:1 row_mask:0xf bank_mask:0xf
	v_fmac_f32_e32 v248, v68, v40
	v_fmac_f32_e32 v249, v69, v41
	v_fmac_f32_e32 v250, v70, v42
	v_fmac_f32_e32 v251, v71, v43
	v_fmac_f32_dpp v248, v40, v64 row_shr:1 row_mask:0xf bank_mask:0xf
	v_fmac_f32_dpp v249, v41, v65 row_shr:1 row_mask:0xf bank_mask:0xf
	v_fmac_f32_dpp v250, v42, v66 row_shr:1 row_mask:0xf bank_mask:0xf
	v_fmac_f32_dpp v251, v43, v67 row_shr:1 row_mask:0xf bank_mask:0xf
	v_fmac_f32_dpp v248, v36, v235 row_mirror row_mask:0xf bank_mask:0xf
	v_fmac_f32_dpp v249, v37, v236 row_mirror row_mask:0xf bank_mask:0xf
	v_fmac_f32_dpp v250, v38, v237 row_mirror row_mask:0xf bank_mask:0xf
	v_fmac_f32_dpp v251, v39, v238 row_mirror row_mask:0xf bank_mask:0xf
	v_pk_mul_f32 v[170:171], v[244:245], v[244:245]
	v_pk_mul_f32 v[172:173], v[246:247], v[246:247]
	v_pk_mul_f32 v[174:175], v[248:249], v[248:249]
	v_pk_mul_f32 v[176:177], v[250:251], v[250:251]
	v_pk_fma_f32 v[170:171], v[170:171], v[96:97], v[216:217] op_sel_hi:[1,0,0]
	v_pk_fma_f32 v[172:173], v[172:173], v[96:97], v[216:217] op_sel_hi:[1,0,0]
	v_pk_fma_f32 v[174:175], v[174:175], v[96:97], v[216:217] op_sel_hi:[1,0,0]
	v_pk_fma_f32 v[176:177], v[176:177], v[96:97], v[216:217] op_sel_hi:[1,0,0]
	v_pk_mul_f32 v[170:171], v[244:245], v[170:171]
	v_pk_mul_f32 v[172:173], v[246:247], v[172:173]
	v_pk_mul_f32 v[174:175], v[248:249], v[174:175]
	v_pk_mul_f32 v[176:177], v[250:251], v[176:177]
	v_exp_f32_e32 v170, v170
	v_exp_f32_e32 v171, v171
	v_exp_f32_e32 v172, v172
	v_exp_f32_e32 v173, v173
	v_exp_f32_e32 v174, v174
	v_exp_f32_e32 v175, v175
	v_exp_f32_e32 v176, v176
	v_exp_f32_e32 v177, v177
	v_pk_add_f32 v[170:171], v[170:171], 1.0 op_sel_hi:[1,0]
	v_pk_add_f32 v[172:173], v[172:173], 1.0 op_sel_hi:[1,0]
	v_pk_add_f32 v[174:175], v[174:175], 1.0 op_sel_hi:[1,0]
	v_pk_add_f32 v[176:177], v[176:177], 1.0 op_sel_hi:[1,0]
	v_rcp_f32_e32 v170, v170
	v_rcp_f32_e32 v171, v171
	v_rcp_f32_e32 v172, v172
	v_rcp_f32_e32 v173, v173
	v_rcp_f32_e32 v174, v174
	v_rcp_f32_e32 v175, v175
	v_rcp_f32_e32 v176, v176
	v_rcp_f32_e32 v177, v177
	v_pk_mul_f32 v[244:245], v[244:245], v[170:171]
	v_pk_mul_f32 v[246:247], v[246:247], v[172:173]
	v_pk_mul_f32 v[248:249], v[248:249], v[174:175]
	v_pk_mul_f32 v[250:251], v[250:251], v[176:177]
	v_pk_mul_f32 v[244:245], v[44:45], v[244:245]
	v_pk_mul_f32 v[246:247], v[46:47], v[246:247]
	v_pk_mul_f32 v[248:249], v[32:33], v[248:249]
	v_pk_mul_f32 v[250:251], v[34:35], v[250:251]
	v_add_u32_e32 v97, 144, v239
	v_cvt_pk_bf16_f32 v244, v244, v245
	v_cvt_pk_bf16_f32 v245, v246, v247
	v_mad_u64_u32 v[242:243], vcc, v97, s2, v[184:185]
	v_cvt_pk_bf16_f32 v246, v248, v249
	v_cvt_pk_bf16_f32 v247, v250, v251
	global_store_dwordx4 v[242:243], v[244:247], off
	s_nop 1
	v_mov_b32_e32 v244, v80
	v_mov_b32_e32 v245, v81
	v_mov_b32_e32 v246, v82
	v_mov_b32_e32 v247, v83
	v_fmac_f32_dpp v244, v12, v158 row_mirror row_mask:0xf bank_mask:0xf
	v_fmac_f32_dpp v245, v13, v159 row_mirror row_mask:0xf bank_mask:0xf
	v_fmac_f32_dpp v246, v14, v160 row_mirror row_mask:0xf bank_mask:0xf
	v_fmac_f32_dpp v247, v15, v161 row_mirror row_mask:0xf bank_mask:0xf
	v_fmac_f32_dpp v244, v28, v92 row_shl:1 row_mask:0xf bank_mask:0xf
	v_fmac_f32_dpp v245, v29, v93 row_shl:1 row_mask:0xf bank_mask:0xf
	v_fmac_f32_dpp v246, v30, v94 row_shl:1 row_mask:0xf bank_mask:0xf
	v_fmac_f32_dpp v247, v31, v95 row_shl:1 row_mask:0xf bank_mask:0xf
	v_fmac_f32_e32 v244, v88, v28
	v_fmac_f32_e32 v245, v89, v29
	v_fmac_f32_e32 v246, v90, v30
	v_fmac_f32_e32 v247, v91, v31
	v_fmac_f32_dpp v244, v28, v84 row_shr:1 row_mask:0xf bank_mask:0xf
	v_fmac_f32_dpp v245, v29, v85 row_shr:1 row_mask:0xf bank_mask:0xf
	v_fmac_f32_dpp v246, v30, v86 row_shr:1 row_mask:0xf bank_mask:0xf
	v_fmac_f32_dpp v247, v31, v87 row_shr:1 row_mask:0xf bank_mask:0xf
	v_fmac_f32_dpp v244, v48, v231 row_mirror row_mask:0xf bank_mask:0xf
	v_fmac_f32_dpp v245, v49, v232 row_mirror row_mask:0xf bank_mask:0xf
	v_fmac_f32_dpp v246, v50, v233 row_mirror row_mask:0xf bank_mask:0xf
	v_fmac_f32_dpp v247, v51, v234 row_mirror row_mask:0xf bank_mask:0xf
	v_mov_b32_e32 v248, v60
	v_mov_b32_e32 v249, v61
	v_mov_b32_e32 v250, v62
	v_mov_b32_e32 v251, v63
	v_fmac_f32_dpp v248, v4, v162 row_mirror row_mask:0xf bank_mask:0xf
	v_fmac_f32_dpp v249, v5, v163 row_mirror row_mask:0xf bank_mask:0xf
	v_fmac_f32_dpp v250, v6, v164 row_mirror row_mask:0xf bank_mask:0xf
	v_fmac_f32_dpp v251, v7, v165 row_mirror row_mask:0xf bank_mask:0xf
	v_fmac_f32_dpp v248, v20, v72 row_shl:1 row_mask:0xf bank_mask:0xf
	v_fmac_f32_dpp v249, v21, v73 row_shl:1 row_mask:0xf bank_mask:0xf
	v_fmac_f32_dpp v250, v22, v74 row_shl:1 row_mask:0xf bank_mask:0xf
	v_fmac_f32_dpp v251, v23, v75 row_shl:1 row_mask:0xf bank_mask:0xf
	v_fmac_f32_e32 v248, v68, v20
	v_fmac_f32_e32 v249, v69, v21
	v_fmac_f32_e32 v250, v70, v22
	v_fmac_f32_e32 v251, v71, v23
	v_fmac_f32_dpp v248, v20, v64 row_shr:1 row_mask:0xf bank_mask:0xf
	v_fmac_f32_dpp v249, v21, v65 row_shr:1 row_mask:0xf bank_mask:0xf
	v_fmac_f32_dpp v250, v22, v66 row_shr:1 row_mask:0xf bank_mask:0xf
	v_fmac_f32_dpp v251, v23, v67 row_shr:1 row_mask:0xf bank_mask:0xf
	v_fmac_f32_dpp v248, v40, v235 row_mirror row_mask:0xf bank_mask:0xf
	v_fmac_f32_dpp v249, v41, v236 row_mirror row_mask:0xf bank_mask:0xf
	v_fmac_f32_dpp v250, v42, v237 row_mirror row_mask:0xf bank_mask:0xf
	v_fmac_f32_dpp v251, v43, v238 row_mirror row_mask:0xf bank_mask:0xf
	v_pk_mul_f32 v[170:171], v[244:245], v[244:245]
	v_pk_mul_f32 v[172:173], v[246:247], v[246:247]
	v_pk_mul_f32 v[174:175], v[248:249], v[248:249]
	v_pk_mul_f32 v[176:177], v[250:251], v[250:251]
	v_pk_fma_f32 v[170:171], v[170:171], v[96:97], v[216:217] op_sel_hi:[1,0,0]
	v_pk_fma_f32 v[172:173], v[172:173], v[96:97], v[216:217] op_sel_hi:[1,0,0]
	v_pk_fma_f32 v[174:175], v[174:175], v[96:97], v[216:217] op_sel_hi:[1,0,0]
	v_pk_fma_f32 v[176:177], v[176:177], v[96:97], v[216:217] op_sel_hi:[1,0,0]
	v_pk_mul_f32 v[170:171], v[244:245], v[170:171]
	v_pk_mul_f32 v[172:173], v[246:247], v[172:173]
	v_pk_mul_f32 v[174:175], v[248:249], v[174:175]
	v_pk_mul_f32 v[176:177], v[250:251], v[176:177]
	v_exp_f32_e32 v170, v170
	v_exp_f32_e32 v171, v171
	v_exp_f32_e32 v172, v172
	v_exp_f32_e32 v173, v173
	v_exp_f32_e32 v174, v174
	v_exp_f32_e32 v175, v175
	v_exp_f32_e32 v176, v176
	v_exp_f32_e32 v177, v177
	v_pk_add_f32 v[170:171], v[170:171], 1.0 op_sel_hi:[1,0]
	v_pk_add_f32 v[172:173], v[172:173], 1.0 op_sel_hi:[1,0]
	v_pk_add_f32 v[174:175], v[174:175], 1.0 op_sel_hi:[1,0]
	v_pk_add_f32 v[176:177], v[176:177], 1.0 op_sel_hi:[1,0]
	v_rcp_f32_e32 v170, v170
	v_rcp_f32_e32 v171, v171
	v_rcp_f32_e32 v172, v172
	v_rcp_f32_e32 v173, v173
	v_rcp_f32_e32 v174, v174
	v_rcp_f32_e32 v175, v175
	v_rcp_f32_e32 v176, v176
	v_rcp_f32_e32 v177, v177
	v_pk_mul_f32 v[244:245], v[244:245], v[170:171]
	v_pk_mul_f32 v[246:247], v[246:247], v[172:173]
	v_pk_mul_f32 v[248:249], v[248:249], v[174:175]
	v_pk_mul_f32 v[250:251], v[250:251], v[176:177]
	v_pk_mul_f32 v[244:245], v[24:25], v[244:245]
	v_pk_mul_f32 v[246:247], v[26:27], v[246:247]
	v_pk_mul_f32 v[248:249], v[16:17], v[248:249]
	v_pk_mul_f32 v[250:251], v[18:19], v[250:251]
	v_add_u32_e32 v97, 160, v239
	v_cvt_pk_bf16_f32 v244, v244, v245
	v_cvt_pk_bf16_f32 v245, v246, v247
	v_mad_u64_u32 v[242:243], vcc, v97, s2, v[184:185]
	v_cvt_pk_bf16_f32 v246, v248, v249
	v_cvt_pk_bf16_f32 v247, v250, v251
	global_store_dwordx4 v[242:243], v[244:247], off
	s_nop 1
	s_and_b64 vcc, exec, s[88:89]
	s_cbranch_vccz .Lgm_z_b1
	ds_read_b128 v[170:173], v225 offset:1024
	ds_read_b128 v[174:177], v225 offset:1040
	s_branch .Lgm_l_b1

.Lgm_l_b1:
	s_waitcnt lgkmcnt(0)
	v_fma_f32 v244, v170, v158, v80
	v_fma_f32 v245, v171, v159, v81
	v_fma_f32 v246, v172, v160, v82
	v_fma_f32 v247, v173, v161, v83
	v_fmac_f32_dpp v244, v12, v92 row_shl:1 row_mask:0xf bank_mask:0xf
	v_fmac_f32_dpp v245, v13, v93 row_shl:1 row_mask:0xf bank_mask:0xf
	v_fmac_f32_dpp v246, v14, v94 row_shl:1 row_mask:0xf bank_mask:0xf
	v_fmac_f32_dpp v247, v15, v95 row_shl:1 row_mask:0xf bank_mask:0xf
	v_fmac_f32_e32 v244, v88, v12
	v_fmac_f32_e32 v245, v89, v13
	v_fmac_f32_e32 v246, v90, v14
	v_fmac_f32_e32 v247, v91, v15
	v_fmac_f32_dpp v244, v12, v84 row_shr:1 row_mask:0xf bank_mask:0xf
	v_fmac_f32_dpp v245, v13, v85 row_shr:1 row_mask:0xf bank_mask:0xf
	v_fmac_f32_dpp v246, v14, v86 row_shr:1 row_mask:0xf bank_mask:0xf
	v_fmac_f32_dpp v247, v15, v87 row_shr:1 row_mask:0xf bank_mask:0xf
	v_fmac_f32_dpp v244, v28, v231 row_mirror row_mask:0xf bank_mask:0xf
	v_fmac_f32_dpp v245, v29, v232 row_mirror row_mask:0xf bank_mask:0xf
	v_fmac_f32_dpp v246, v30, v233 row_mirror row_mask:0xf bank_mask:0xf
	v_fmac_f32_dpp v247, v31, v234 row_mirror row_mask:0xf bank_mask:0xf
	v_fma_f32 v248, v174, v162, v60
	v_fma_f32 v249, v175, v163, v61
	v_fma_f32 v250, v176, v164, v62
	v_fma_f32 v251, v177, v165, v63
	v_fmac_f32_dpp v248, v4, v72 row_shl:1 row_mask:0xf bank_mask:0xf
	v_fmac_f32_dpp v249, v5, v73 row_shl:1 row_mask:0xf bank_mask:0xf
	v_fmac_f32_dpp v250, v6, v74 row_shl:1 row_mask:0xf bank_mask:0xf
	v_fmac_f32_dpp v251, v7, v75 row_shl:1 row_mask:0xf bank_mask:0xf
	v_fmac_f32_e32 v248, v68, v4
	v_fmac_f32_e32 v249, v69, v5
	v_fmac_f32_e32 v250, v70, v6
	v_fmac_f32_e32 v251, v71, v7
	v_fmac_f32_dpp v248, v4, v64 row_shr:1 row_mask:0xf bank_mask:0xf
	v_fmac_f32_dpp v249, v5, v65 row_shr:1 row_mask:0xf bank_mask:0xf
	v_fmac_f32_dpp v250, v6, v66 row_shr:1 row_mask:0xf bank_mask:0xf
	v_fmac_f32_dpp v251, v7, v67 row_shr:1 row_mask:0xf bank_mask:0xf
	v_fmac_f32_dpp v248, v20, v235 row_mirror row_mask:0xf bank_mask:0xf
	v_fmac_f32_dpp v249, v21, v236 row_mirror row_mask:0xf bank_mask:0xf
	v_fmac_f32_dpp v250, v22, v237 row_mirror row_mask:0xf bank_mask:0xf
	v_fmac_f32_dpp v251, v23, v238 row_mirror row_mask:0xf bank_mask:0xf
	v_pk_mul_f32 v[170:171], v[244:245], v[244:245]
	v_pk_mul_f32 v[172:173], v[246:247], v[246:247]
	v_pk_mul_f32 v[174:175], v[248:249], v[248:249]
	v_pk_mul_f32 v[176:177], v[250:251], v[250:251]
	v_pk_fma_f32 v[170:171], v[170:171], v[96:97], v[216:217] op_sel_hi:[1,0,0]
	v_pk_fma_f32 v[172:173], v[172:173], v[96:97], v[216:217] op_sel_hi:[1,0,0]
	v_pk_fma_f32 v[174:175], v[174:175], v[96:97], v[216:217] op_sel_hi:[1,0,0]
	v_pk_fma_f32 v[176:177], v[176:177], v[96:97], v[216:217] op_sel_hi:[1,0,0]
	v_pk_mul_f32 v[170:171], v[244:245], v[170:171]
	v_pk_mul_f32 v[172:173], v[246:247], v[172:173]
	v_pk_mul_f32 v[174:175], v[248:249], v[174:175]
	v_pk_mul_f32 v[176:177], v[250:251], v[176:177]
	v_exp_f32_e32 v170, v170
	v_exp_f32_e32 v171, v171
	v_exp_f32_e32 v172, v172
	v_exp_f32_e32 v173, v173
	v_exp_f32_e32 v174, v174
	v_exp_f32_e32 v175, v175
	v_exp_f32_e32 v176, v176
	v_exp_f32_e32 v177, v177
	v_pk_add_f32 v[170:171], v[170:171], 1.0 op_sel_hi:[1,0]
	v_pk_add_f32 v[172:173], v[172:173], 1.0 op_sel_hi:[1,0]
	v_pk_add_f32 v[174:175], v[174:175], 1.0 op_sel_hi:[1,0]
	v_pk_add_f32 v[176:177], v[176:177], 1.0 op_sel_hi:[1,0]
	v_rcp_f32_e32 v170, v170
	v_rcp_f32_e32 v171, v171
	v_rcp_f32_e32 v172, v172
	v_rcp_f32_e32 v173, v173
	v_rcp_f32_e32 v174, v174
	v_rcp_f32_e32 v175, v175
	v_rcp_f32_e32 v176, v176
	v_rcp_f32_e32 v177, v177
	v_pk_mul_f32 v[244:245], v[244:245], v[170:171]
	v_pk_mul_f32 v[246:247], v[246:247], v[172:173]
	v_pk_mul_f32 v[248:249], v[248:249], v[174:175]
	v_pk_mul_f32 v[250:251], v[250:251], v[176:177]
	v_pk_mul_f32 v[244:245], v[8:9], v[244:245]
	v_pk_mul_f32 v[246:247], v[10:11], v[246:247]
	v_pk_mul_f32 v[248:249], v[0:1], v[248:249]
	v_pk_mul_f32 v[250:251], v[2:3], v[250:251]
	v_add_u32_e32 v97, 176, v239
	v_cvt_pk_bf16_f32 v244, v244, v245
	v_cvt_pk_bf16_f32 v245, v246, v247
	v_mad_u64_u32 v[242:243], vcc, v97, s2, v[184:185]
	v_cvt_pk_bf16_f32 v246, v248, v249
	v_cvt_pk_bf16_f32 v247, v250, v251
	global_store_dwordx4 v[242:243], v[244:247], off
	s_nop 1
	s_andn2_b64 vcc, exec, s[42:43]
	s_movk_i32 s43, 0x90
	s_mov_b64 s[0:1], -1
	s_waitcnt lgkmcnt(0)
	s_barrier
	s_cbranch_vccnz .LBB0_624
	v_readlane_b32 s0, v255, 12
	v_readlane_b32 s1, v255, 13
	s_andn2_b64 vcc, exec, s[0:1]
	s_cbranch_vccnz .LBB0_623
	s_barrier
	s_branch .LBB0_623
